# LN3 row_finalize hand-rewritten: wig columns resident in registers (no per-row LDS re-reads), b_in hoisted, 8 wave sums interleaved without hazard nops
# speedup vs baseline: 1.0114x; 1.0039x over previous
; #define LAS __attribute__((address_space(3)))
; __device__ __forceinline__ void row_finalize(CArgs& A, Frame& F, int m, const f32x4 (&v)[4], int Ln) {
;     ...
;     const LAS float* wig = (const LAS float*)(F.lds + WIG_OFF); const float* b_in = A.in[10] + (size_t)Ln * DIN + 3072;
;     float r[8];
; #pragma unroll
;     for (int c = 0; c < 8; ++c) { float s = 0.f;
; #pragma unroll
;         for (int j = 0; j < 4; ++j) { const f32x4 w = *(const LAS f32x4*)(wig + c * 1024 + RCOL(F.lane, j)); s += (v[j][0] * w[0] + v[j][1] * w[1]) + (v[j][2] * w[2] + v[j][3] * w[3]); }
; __global__ void __launch_bounds__(NT, 2) fwd(const Args args) {
;     ...
;         if (IN(pb + 10)) { PHASE_BEGIN
;             const float* g = A.in[17] + ((size_t)L * 3 + 2) * D; const float* bb = A.in[18] + ((size_t)L * 3 + 2) * D; const bf16* X = WSP(bf16, WS_XB);
;             if (L + 1 < DEPTH) { stage_wig(A, F, L + 1); __syncthreads(); }
;             int m0, m1; row_range(F, m0, m1);
;             for (int m = m0; m < m1; m += 4) { u32x4 r[4][2];
.LBB0_1693:
	v_mov_b32_e32 v1, s6
	v_lshl_add_u32 v1, s8, 3, v1
	v_readlane_b32 s12, v253, 53
	v_readlane_b32 s8, v253, 52
	s_nop 0
	v_min_i32_e32 v3, s12, v1
	v_mul_lo_u32 v4, s8, v1
	v_readfirstlane_b32 s11, v3
	v_readfirstlane_b32 s16, v4
	v_add_u32_e32 v3, v4, v3
	v_mov_b32_e32 v4, s8
	v_cmp_gt_i32_e32 vcc, s12, v1
	v_readfirstlane_b32 s6, v3
	s_nop 0
	v_addc_co_u32_e32 v1, vcc, v3, v4, vcc
	v_cmp_ge_i32_e32 vcc, v3, v1
	s_and_b64 s[12:13], vcc, exec
	v_readfirstlane_b32 s8, v1
	s_cbranch_scc1 .LBB0_1723
	s_mul_hi_i32 s12, s10, 0x3000
	s_mulk_i32 s10, 0x3000
	s_add_u32 s10, s10, 0x2000
	s_addc_u32 s12, s12, 0
	v_lshlrev_b32_e32 v4, 3, v0
	s_waitcnt lgkmcnt(0)
	s_add_u32 s14, s40, s10
	v_ashrrev_i32_e32 v5, 31, v4
	s_addc_u32 s15, s41, s12
	v_lshlrev_b64 v[6:7], 1, v[4:5]
	s_add_u32 s18, s42, s10
	v_lshl_add_u64 v[8:9], s[58:59], 0, v[6:7]
	s_mov_b64 s[26:27], 0xb880000
	s_addc_u32 s19, s43, s12
	v_lshl_add_u64 v[52:53], v[8:9], 0, s[26:27]
	v_lshlrev_b64 v[54:55], 2, v[4:5]
	s_mul_hi_i32 s13, s7, 0x6820
	s_mul_i32 s26, s7, 0x6820
	s_ashr_i32 s7, s6, 31
	s_add_i32 s12, s8, -1
	v_lshl_add_u64 v[56:57], s[14:15], 0, v[54:55]
	s_lshl_b64 s[14:15], s[6:7], 12
	s_add_u32 s14, s56, s14
	v_lshl_add_u64 v[58:59], s[18:19], 0, v[54:55]
	s_addc_u32 s15, s57, s15
	s_lshl_b64 s[18:19], s[6:7], 5
	v_ashrrev_i32_e32 v1, 31, v0
	s_add_u32 s18, s18, 0x1b000000
	s_addc_u32 s19, s19, 0
	v_lshlrev_b64 v[4:5], 2, v[0:1]
	v_lshl_add_u64 v[60:61], s[18:19], 0, v[4:5]
	s_lshl_b64 s[18:19], s[6:7], 11
	s_add_i32 s7, s11, s16
	s_add_i32 s10, s7, 3
	s_ashr_i32 s11, s10, 31
	s_lshl_b64 s[16:17], s[10:11], 5
	s_add_u32 s16, s16, 0x1b000000
	s_addc_u32 s17, s17, 0
	s_add_i32 s28, s7, 1
	v_lshl_add_u64 v[64:65], s[16:17], 0, v[4:5]
	s_lshl_b64 s[16:17], s[10:11], 11
	s_ashr_i32 s29, s28, 31
	v_lshl_add_u64 v[66:67], s[16:17], 0, v[6:7]
	s_lshl_b64 s[16:17], s[28:29], 12
	s_add_u32 s16, s56, s16
	s_addc_u32 s17, s57, s17
	s_lshl_b64 s[10:11], s[10:11], 12
	v_lshl_add_u64 v[62:63], s[18:19], 0, v[6:7]
	s_add_u32 s18, s56, s10
	s_addc_u32 s19, s57, s11
	s_add_i32 s10, s7, 2
	s_ashr_i32 s11, s10, 31
	s_lshl_b64 s[34:35], s[10:11], 5
	s_add_u32 s34, s34, 0x1b000000
	s_addc_u32 s35, s35, 0
	v_lshl_add_u64 v[68:69], s[34:35], 0, v[4:5]
	s_lshl_b64 s[34:35], s[10:11], 11
	v_lshl_add_u64 v[70:71], s[34:35], 0, v[6:7]
	s_lshl_b64 s[34:35], s[28:29], 11
	s_lshl_b64 s[10:11], s[10:11], 12
	v_lshl_add_u64 v[72:73], s[34:35], 0, v[6:7]
	s_add_u32 s34, s56, s10
	s_addc_u32 s35, s57, s11
	s_lshl_b64 s[10:11], s[28:29], 5
	s_add_u32 s10, s10, 0x1b000000
	s_addc_u32 s11, s11, 0
	v_lshlrev_b32_e32 v3, 5, v0
	v_cmp_gt_i32_e64 s[38:39], 8, v0
	v_cmp_eq_u32_e64 s[40:41], 1, v0
	v_cmp_eq_u32_e64 s[42:43], 2, v0
	v_cmp_eq_u32_e64 s[44:45], 3, v0
	v_cmp_eq_u32_e64 s[46:47], 4, v0
	v_cmp_eq_u32_e64 s[48:49], 5, v0
	v_cmp_eq_u32_e64 s[50:51], 6, v0
	v_cmp_eq_u32_e64 s[52:53], 7, v0
	v_lshl_add_u64 v[74:75], s[10:11], 0, v[4:5]
	s_and_b64 vcc, exec, s[4:5]
	s_cbranch_vccnz .Lwres_skip
	s_load_dwordx2 s[66:67], s[2:3], 0x50
	v_add_u32_e32 v198, 0x12000, v3
	ds_read_b128 v[94:97], v198 offset:0
	ds_read_b128 v[98:101], v198 offset:16
	ds_read_b128 v[102:105], v198 offset:2048
	ds_read_b128 v[106:109], v198 offset:2064
	ds_read_b128 v[110:113], v198 offset:4096
	ds_read_b128 v[114:117], v198 offset:4112
	ds_read_b128 v[118:121], v198 offset:6144
	ds_read_b128 v[122:125], v198 offset:6160
	s_waitcnt lgkmcnt(0)
	ds_read_b128 v[126:129], v198 offset:8192
	ds_read_b128 v[130:133], v198 offset:8208
	ds_read_b128 v[134:137], v198 offset:10240
	ds_read_b128 v[138:141], v198 offset:10256
	ds_read_b128 v[142:145], v198 offset:12288
	ds_read_b128 v[146:149], v198 offset:12304
	ds_read_b128 v[150:153], v198 offset:14336
	ds_read_b128 v[154:157], v198 offset:14352
	s_waitcnt lgkmcnt(0)
	ds_read_b128 v[158:161], v198 offset:16384
	ds_read_b128 v[162:165], v198 offset:16400
	ds_read_b128 v[166:169], v198 offset:18432
	ds_read_b128 v[170:173], v198 offset:18448
	ds_read_b128 v[174:177], v198 offset:20480
	ds_read_b128 v[178:181], v198 offset:20496
	ds_read_b128 v[182:185], v198 offset:22528
	ds_read_b128 v[186:189], v198 offset:22544
	s_waitcnt lgkmcnt(0)
	ds_read_b128 v[190:193], v198 offset:24576
	ds_read_b128 v[194:197], v198 offset:24592
	ds_read_b128 v[202:205], v198 offset:26624
	ds_read_b128 v[206:209], v198 offset:26640
	ds_read_b128 v[210:213], v198 offset:28672
	ds_read_b128 v[214:217], v198 offset:28688
	ds_read_b128 v[218:221], v198 offset:30720
	ds_read_b128 v[222:225], v198 offset:30736
	s_waitcnt lgkmcnt(0)
	s_add_u32 s66, s66, s26
	s_addc_u32 s67, s67, s13
	s_add_u32 s66, s66, 0x3000
	s_addc_u32 s67, s67, 0
	v_lshl_add_u64 v[198:199], v[0:1], 2, s[66:67]
	global_load_dword v200, v[198:199], off
.Lwres_skip:
	s_branch .LBB0_1697
.LBB0_1695:
	s_or_b64 exec, exec, s[10:11]

; #define LAS __attribute__((address_space(3)))
; __device__ __forceinline__ void row_finalize(CArgs& A, Frame& F, int m, const f32x4 (&v)[4], int Ln) {
;     row_store_bf(WSP(bf16, WS_X) + (size_t)m * D, F.lane, v);
;     const LAS float* wig = (const LAS float*)(F.lds + WIG_OFF); const float* b_in = A.in[10] + (size_t)Ln * DIN + 3072;
;     float r[8];
; #pragma unroll
;     for (int c = 0; c < 8; ++c) { float s = 0.f;
; #pragma unroll
;         for (int j = 0; j < 4; ++j) { const f32x4 w = *(const LAS f32x4*)(wig + c * 1024 + RCOL(F.lane, j)); s += (v[j][0] * w[0] + v[j][1] * w[1]) + (v[j][2] * w[2] + v[j][3] * w[3]); }
.LBB0_1701:
	v_lshl_add_u64 v[238:239], s[58:59], 0, v[62:63]
	s_mov_b64 s[10:11], 0x7680000
	v_cvt_pk_bf16_f32 v240, v32, v33
	v_cvt_pk_bf16_f32 v241, v34, v35
	v_cvt_pk_bf16_f32 v242, v28, v29
	v_cvt_pk_bf16_f32 v243, v30, v31
	v_lshl_add_u64 v[238:239], v[238:239], 0, s[10:11]
	v_cvt_pk_bf16_f32 v244, v44, v45
	v_cvt_pk_bf16_f32 v245, v46, v47
	v_cvt_pk_bf16_f32 v246, v36, v37
	v_cvt_pk_bf16_f32 v247, v38, v39
	global_store_dwordx4 v[238:239], v[240:243], off
	global_store_dwordx4 v[238:239], v[244:247], off offset:1024
	v_lshl_add_u64 v[198:199], s[58:59], 0, v[60:61]
	v_mul_f32_e32 v249, v33, v95
	v_mul_f32_e32 v250, v35, v97
	v_fmac_f32_e32 v249, v32, v94
	v_fmac_f32_e32 v250, v34, v96
	v_add_f32_e32 v249, v249, v250
	v_add_f32_e32 v227, 0, v249
	v_mul_f32_e32 v249, v29, v99
	v_mul_f32_e32 v250, v31, v101
	v_fmac_f32_e32 v249, v28, v98
	v_fmac_f32_e32 v250, v30, v100
	v_add_f32_e32 v249, v249, v250
	v_add_f32_e32 v227, v227, v249
	v_mul_f32_e32 v249, v45, v103
	v_mul_f32_e32 v250, v47, v105
	v_fmac_f32_e32 v249, v44, v102
	v_fmac_f32_e32 v250, v46, v104
	v_add_f32_e32 v249, v249, v250
	v_add_f32_e32 v227, v227, v249
	v_mul_f32_e32 v249, v37, v107
	v_mul_f32_e32 v250, v39, v109
	v_fmac_f32_e32 v249, v36, v106
	v_fmac_f32_e32 v250, v38, v108
	v_add_f32_e32 v249, v249, v250
	v_add_f32_e32 v227, v227, v249
	v_mul_f32_e32 v249, v33, v111
	v_mul_f32_e32 v250, v35, v113
	v_fmac_f32_e32 v249, v32, v110
	v_fmac_f32_e32 v250, v34, v112
	v_add_f32_e32 v249, v249, v250
	v_add_f32_e32 v228, 0, v249
	v_mul_f32_e32 v249, v29, v115
	v_mul_f32_e32 v250, v31, v117
	v_fmac_f32_e32 v249, v28, v114
	v_fmac_f32_e32 v250, v30, v116
	v_add_f32_e32 v249, v249, v250
	v_add_f32_e32 v228, v228, v249
	v_mul_f32_e32 v249, v45, v119
	v_mul_f32_e32 v250, v47, v121
	v_fmac_f32_e32 v249, v44, v118
	v_fmac_f32_e32 v250, v46, v120
	v_add_f32_e32 v249, v249, v250
	v_add_f32_e32 v228, v228, v249
	v_mul_f32_e32 v249, v37, v123
	v_mul_f32_e32 v250, v39, v125
	v_fmac_f32_e32 v249, v36, v122
	v_fmac_f32_e32 v250, v38, v124
	v_add_f32_e32 v249, v249, v250
	v_add_f32_e32 v228, v228, v249
	v_mul_f32_e32 v249, v33, v127
	v_mul_f32_e32 v250, v35, v129
	v_fmac_f32_e32 v249, v32, v126
	v_fmac_f32_e32 v250, v34, v128
	v_add_f32_e32 v249, v249, v250
	v_add_f32_e32 v229, 0, v249
	v_mul_f32_e32 v249, v29, v131
	v_mul_f32_e32 v250, v31, v133
	v_fmac_f32_e32 v249, v28, v130
	v_fmac_f32_e32 v250, v30, v132
	v_add_f32_e32 v249, v249, v250
	v_add_f32_e32 v229, v229, v249
	v_mul_f32_e32 v249, v45, v135
	v_mul_f32_e32 v250, v47, v137
	v_fmac_f32_e32 v249, v44, v134
	v_fmac_f32_e32 v250, v46, v136
	v_add_f32_e32 v249, v249, v250
	v_add_f32_e32 v229, v229, v249
	v_mul_f32_e32 v249, v37, v139
	v_mul_f32_e32 v250, v39, v141
	v_fmac_f32_e32 v249, v36, v138
	v_fmac_f32_e32 v250, v38, v140
	v_add_f32_e32 v249, v249, v250
	v_add_f32_e32 v229, v229, v249
	v_mul_f32_e32 v249, v33, v143
	v_mul_f32_e32 v250, v35, v145
	v_fmac_f32_e32 v249, v32, v142
	v_fmac_f32_e32 v250, v34, v144
	v_add_f32_e32 v249, v249, v250
	v_add_f32_e32 v230, 0, v249
	v_mul_f32_e32 v249, v29, v147
	v_mul_f32_e32 v250, v31, v149
	v_fmac_f32_e32 v249, v28, v146
	v_fmac_f32_e32 v250, v30, v148
	v_add_f32_e32 v249, v249, v250
	v_add_f32_e32 v230, v230, v249
	v_mul_f32_e32 v249, v45, v151
	v_mul_f32_e32 v250, v47, v153
	v_fmac_f32_e32 v249, v44, v150
	v_fmac_f32_e32 v250, v46, v152
	v_add_f32_e32 v249, v249, v250
	v_add_f32_e32 v230, v230, v249
	v_mul_f32_e32 v249, v37, v155
	v_mul_f32_e32 v250, v39, v157
	v_fmac_f32_e32 v249, v36, v154
	v_fmac_f32_e32 v250, v38, v156
	v_add_f32_e32 v249, v249, v250
	v_add_f32_e32 v230, v230, v249
	v_mul_f32_e32 v249, v33, v159
	v_mul_f32_e32 v250, v35, v161
	v_fmac_f32_e32 v249, v32, v158
	v_fmac_f32_e32 v250, v34, v160
	v_add_f32_e32 v249, v249, v250
	v_add_f32_e32 v231, 0, v249
	v_mul_f32_e32 v249, v29, v163
	v_mul_f32_e32 v250, v31, v165
	v_fmac_f32_e32 v249, v28, v162
	v_fmac_f32_e32 v250, v30, v164
	v_add_f32_e32 v249, v249, v250
	v_add_f32_e32 v231, v231, v249
	v_mul_f32_e32 v249, v45, v167
	v_mul_f32_e32 v250, v47, v169
	v_fmac_f32_e32 v249, v44, v166
	v_fmac_f32_e32 v250, v46, v168
	v_add_f32_e32 v249, v249, v250
	v_add_f32_e32 v231, v231, v249
	v_mul_f32_e32 v249, v37, v171
	v_mul_f32_e32 v250, v39, v173
	v_fmac_f32_e32 v249, v36, v170
	v_fmac_f32_e32 v250, v38, v172
	v_add_f32_e32 v249, v249, v250
	v_add_f32_e32 v231, v231, v249
	v_mul_f32_e32 v249, v33, v175
	v_mul_f32_e32 v250, v35, v177
	v_fmac_f32_e32 v249, v32, v174
	v_fmac_f32_e32 v250, v34, v176
	v_add_f32_e32 v249, v249, v250
	v_add_f32_e32 v232, 0, v249
	v_mul_f32_e32 v249, v29, v179
	v_mul_f32_e32 v250, v31, v181
	v_fmac_f32_e32 v249, v28, v178
	v_fmac_f32_e32 v250, v30, v180
	v_add_f32_e32 v249, v249, v250
	v_add_f32_e32 v232, v232, v249
	v_mul_f32_e32 v249, v45, v183
	v_mul_f32_e32 v250, v47, v185
	v_fmac_f32_e32 v249, v44, v182
	v_fmac_f32_e32 v250, v46, v184
	v_add_f32_e32 v249, v249, v250
	v_add_f32_e32 v232, v232, v249
	v_mul_f32_e32 v249, v37, v187
	v_mul_f32_e32 v250, v39, v189
	v_fmac_f32_e32 v249, v36, v186
	v_fmac_f32_e32 v250, v38, v188
	v_add_f32_e32 v249, v249, v250
	v_add_f32_e32 v232, v232, v249
	v_mul_f32_e32 v249, v33, v191
	v_mul_f32_e32 v250, v35, v193
	v_fmac_f32_e32 v249, v32, v190
	v_fmac_f32_e32 v250, v34, v192
	v_add_f32_e32 v249, v249, v250
	v_add_f32_e32 v233, 0, v249
	v_mul_f32_e32 v249, v29, v195
	v_mul_f32_e32 v250, v31, v197
	v_fmac_f32_e32 v249, v28, v194
	v_fmac_f32_e32 v250, v30, v196
	v_add_f32_e32 v249, v249, v250
	v_add_f32_e32 v233, v233, v249
	v_mul_f32_e32 v249, v45, v203
	v_mul_f32_e32 v250, v47, v205
	v_fmac_f32_e32 v249, v44, v202
	v_fmac_f32_e32 v250, v46, v204
; template <int CTRL, int ROWMASK> __device__ __forceinline__ float dppf(float v) { return __builtin_bit_cast(float, __builtin_amdgcn_update_dpp(0, __builtin_bit_cast(int, v), CTRL, ROWMASK, 0xf, false)); }
; __device__ __forceinline__ float dpp_sum63(float v) {
;     v += dppf<0xB1, 0xf>(v); v += dppf<0x4E, 0xf>(v); v += dppf<0x141, 0xf>(v); v += dppf<0x140, 0xf>(v);
;     v += dppf<0x142, 0xa>(v); v += dppf<0x143, 0xc>(v); return v;
; }
; template <int CTRL, int ROWMASK> __device__ __forceinline__ float dppm(float v) { return __builtin_bit_cast(float, __builtin_amdgcn_update_dpp(__builtin_bit_cast(int, v), __builtin_bit_cast(int, v), CTRL, ROWMASK, 0xf, false)); }
; __device__ __forceinline__ float rdlane(float v, int l) { return __builtin_bit_cast(float, __builtin_amdgcn_readlane(__builtin_bit_cast(int, v), l)); }
; __device__ __forceinline__ float wave_sum(float v) { return rdlane(dpp_sum63(v), 63); }
; __device__ __forceinline__ void row_finalize(CArgs& A, Frame& F, int m, const f32x4 (&v)[4], int Ln) {
;     ...
;         r[c] = wave_sum(s); if (c & 1) asm volatile("" ::: "memory"); }
;     if (F.lane < 8) { float x = r[0];
; #pragma unroll
;         for (int c = 1; c < 8; ++c) x = (F.lane == c) ? r[c] : x;
;         WSP(float, WS_IGFG)[(size_t)m * 8 + F.lane] = x + b_in[F.lane]; }
	v_add_f32_e32 v249, v249, v250
	v_add_f32_e32 v233, v233, v249
	v_mul_f32_e32 v249, v37, v207
	v_mul_f32_e32 v250, v39, v209
	v_fmac_f32_e32 v249, v36, v206
	v_fmac_f32_e32 v250, v38, v208
	v_add_f32_e32 v249, v249, v250
	v_add_f32_e32 v233, v233, v249
	v_mul_f32_e32 v249, v33, v211
	v_mul_f32_e32 v250, v35, v213
	v_fmac_f32_e32 v249, v32, v210
	v_fmac_f32_e32 v250, v34, v212
	v_add_f32_e32 v249, v249, v250
	v_add_f32_e32 v248, 0, v249
	v_mul_f32_e32 v249, v29, v215
	v_mul_f32_e32 v250, v31, v217
	v_fmac_f32_e32 v249, v28, v214
	v_fmac_f32_e32 v250, v30, v216
	v_add_f32_e32 v249, v249, v250
	v_add_f32_e32 v248, v248, v249
	v_mul_f32_e32 v249, v45, v219
	v_mul_f32_e32 v250, v47, v221
	v_fmac_f32_e32 v249, v44, v218
	v_fmac_f32_e32 v250, v46, v220
	v_add_f32_e32 v249, v249, v250
	v_add_f32_e32 v248, v248, v249
	v_mul_f32_e32 v249, v37, v223
	v_mul_f32_e32 v250, v39, v225
	v_fmac_f32_e32 v249, v36, v222
	v_fmac_f32_e32 v250, v38, v224
	v_add_f32_e32 v249, v249, v250
	v_add_f32_e32 v248, v248, v249
	v_add_f32_dpp v227, v227, v227 quad_perm:[1,0,3,2] row_mask:0xf bank_mask:0xf bound_ctrl:1
	v_add_f32_dpp v228, v228, v228 quad_perm:[1,0,3,2] row_mask:0xf bank_mask:0xf bound_ctrl:1
	v_add_f32_dpp v229, v229, v229 quad_perm:[1,0,3,2] row_mask:0xf bank_mask:0xf bound_ctrl:1
	v_add_f32_dpp v230, v230, v230 quad_perm:[1,0,3,2] row_mask:0xf bank_mask:0xf bound_ctrl:1
	v_add_f32_dpp v231, v231, v231 quad_perm:[1,0,3,2] row_mask:0xf bank_mask:0xf bound_ctrl:1
	v_add_f32_dpp v232, v232, v232 quad_perm:[1,0,3,2] row_mask:0xf bank_mask:0xf bound_ctrl:1
	v_add_f32_dpp v233, v233, v233 quad_perm:[1,0,3,2] row_mask:0xf bank_mask:0xf bound_ctrl:1
	v_add_f32_dpp v248, v248, v248 quad_perm:[1,0,3,2] row_mask:0xf bank_mask:0xf bound_ctrl:1
	v_add_f32_dpp v227, v227, v227 quad_perm:[2,3,0,1] row_mask:0xf bank_mask:0xf bound_ctrl:1
	v_add_f32_dpp v228, v228, v228 quad_perm:[2,3,0,1] row_mask:0xf bank_mask:0xf bound_ctrl:1
	v_add_f32_dpp v229, v229, v229 quad_perm:[2,3,0,1] row_mask:0xf bank_mask:0xf bound_ctrl:1
	v_add_f32_dpp v230, v230, v230 quad_perm:[2,3,0,1] row_mask:0xf bank_mask:0xf bound_ctrl:1
	v_add_f32_dpp v231, v231, v231 quad_perm:[2,3,0,1] row_mask:0xf bank_mask:0xf bound_ctrl:1
	v_add_f32_dpp v232, v232, v232 quad_perm:[2,3,0,1] row_mask:0xf bank_mask:0xf bound_ctrl:1
	v_add_f32_dpp v233, v233, v233 quad_perm:[2,3,0,1] row_mask:0xf bank_mask:0xf bound_ctrl:1
	v_add_f32_dpp v248, v248, v248 quad_perm:[2,3,0,1] row_mask:0xf bank_mask:0xf bound_ctrl:1
	v_add_f32_dpp v227, v227, v227 row_half_mirror row_mask:0xf bank_mask:0xf bound_ctrl:1
	v_add_f32_dpp v228, v228, v228 row_half_mirror row_mask:0xf bank_mask:0xf bound_ctrl:1
	v_add_f32_dpp v229, v229, v229 row_half_mirror row_mask:0xf bank_mask:0xf bound_ctrl:1
	v_add_f32_dpp v230, v230, v230 row_half_mirror row_mask:0xf bank_mask:0xf bound_ctrl:1
	v_add_f32_dpp v231, v231, v231 row_half_mirror row_mask:0xf bank_mask:0xf bound_ctrl:1
	v_add_f32_dpp v232, v232, v232 row_half_mirror row_mask:0xf bank_mask:0xf bound_ctrl:1
	v_add_f32_dpp v233, v233, v233 row_half_mirror row_mask:0xf bank_mask:0xf bound_ctrl:1
	v_add_f32_dpp v248, v248, v248 row_half_mirror row_mask:0xf bank_mask:0xf bound_ctrl:1
	v_add_f32_dpp v227, v227, v227 row_mirror row_mask:0xf bank_mask:0xf bound_ctrl:1
	v_add_f32_dpp v228, v228, v228 row_mirror row_mask:0xf bank_mask:0xf bound_ctrl:1
	v_add_f32_dpp v229, v229, v229 row_mirror row_mask:0xf bank_mask:0xf bound_ctrl:1
	v_add_f32_dpp v230, v230, v230 row_mirror row_mask:0xf bank_mask:0xf bound_ctrl:1
	v_add_f32_dpp v231, v231, v231 row_mirror row_mask:0xf bank_mask:0xf bound_ctrl:1
	v_add_f32_dpp v232, v232, v232 row_mirror row_mask:0xf bank_mask:0xf bound_ctrl:1
	v_add_f32_dpp v233, v233, v233 row_mirror row_mask:0xf bank_mask:0xf bound_ctrl:1
	v_add_f32_dpp v248, v248, v248 row_mirror row_mask:0xf bank_mask:0xf bound_ctrl:1
	v_add_f32_dpp v227, v227, v227 row_bcast:15 row_mask:0xa bank_mask:0xf
	v_add_f32_dpp v228, v228, v228 row_bcast:15 row_mask:0xa bank_mask:0xf
	v_add_f32_dpp v229, v229, v229 row_bcast:15 row_mask:0xa bank_mask:0xf
	v_add_f32_dpp v230, v230, v230 row_bcast:15 row_mask:0xa bank_mask:0xf
	v_add_f32_dpp v231, v231, v231 row_bcast:15 row_mask:0xa bank_mask:0xf
	v_add_f32_dpp v232, v232, v232 row_bcast:15 row_mask:0xa bank_mask:0xf
	v_add_f32_dpp v233, v233, v233 row_bcast:15 row_mask:0xa bank_mask:0xf
	v_add_f32_dpp v248, v248, v248 row_bcast:15 row_mask:0xa bank_mask:0xf
	v_add_f32_dpp v227, v227, v227 row_bcast:31 row_mask:0xc bank_mask:0xf
	v_add_f32_dpp v228, v228, v228 row_bcast:31 row_mask:0xc bank_mask:0xf
	v_add_f32_dpp v229, v229, v229 row_bcast:31 row_mask:0xc bank_mask:0xf
	v_add_f32_dpp v230, v230, v230 row_bcast:31 row_mask:0xc bank_mask:0xf
	v_add_f32_dpp v231, v231, v231 row_bcast:31 row_mask:0xc bank_mask:0xf
	v_add_f32_dpp v232, v232, v232 row_bcast:31 row_mask:0xc bank_mask:0xf
	v_add_f32_dpp v233, v233, v233 row_bcast:31 row_mask:0xc bank_mask:0xf
	v_add_f32_dpp v248, v248, v248 row_bcast:31 row_mask:0xc bank_mask:0xf
	v_readlane_b32 s29, v227, 63
	v_readlane_b32 s36, v228, 63
	v_readlane_b32 s37, v229, 63
	v_readlane_b32 s56, v230, 63
	v_readlane_b32 s57, v231, 63
	v_readlane_b32 s60, v232, 63
	v_readlane_b32 s61, v233, 63
	v_readlane_b32 s64, v248, 63
	v_writelane_b32 v251, s29, 0
	v_writelane_b32 v251, s36, 1
	v_writelane_b32 v251, s37, 2
	v_writelane_b32 v251, s56, 3
	v_writelane_b32 v251, s57, 4
	v_writelane_b32 v251, s60, 5
	v_writelane_b32 v251, s61, 6
	v_writelane_b32 v251, s64, 7
	s_and_saveexec_b64 s[10:11], s[38:39]
	v_add_f32_e32 v251, v251, v200
	global_store_dword v[198:199], v251, off

; #define LAS __attribute__((address_space(3)))
; __device__ __forceinline__ unsigned pk2(float lo, float hi) { unsigned r; asm volatile("v_cvt_pk_bf16_f32 %0, %1, %2" : "=v"(r) : "v"(lo), "v"(hi)); return r; }
; __device__ __forceinline__ float wave_sum(float v) { return rdlane(dpp_sum63(v), 63); }
; __device__ __forceinline__ void row_store_bf(bf16* p, int lane, const f32x4 (&v)[4]) {
; #pragma unroll
;     for (int j = 0; j < 2; ++j) { u32x4 w; w.x = pk2(v[2 * j][0], v[2 * j][1]); w.y = pk2(v[2 * j][2], v[2 * j][3]); w.z = pk2(v[2 * j + 1][0], v[2 * j + 1][1]); w.w = pk2(v[2 * j + 1][2], v[2 * j + 1][3]); *(u32x4*)(p + 8 * lane + 512 * j) = w; }
; }
; __device__ __forceinline__ void row_finalize(CArgs& A, Frame& F, int m, const f32x4 (&v)[4], int Ln) {
;     row_store_bf(WSP(bf16, WS_X) + (size_t)m * D, F.lane, v);
;     const LAS float* wig = (const LAS float*)(F.lds + WIG_OFF); const float* b_in = A.in[10] + (size_t)Ln * DIN + 3072;
;     float r[8];
; #pragma unroll
;     for (int c = 0; c < 8; ++c) { float s = 0.f;
; #pragma unroll
;         for (int j = 0; j < 4; ++j) { const f32x4 w = *(const LAS f32x4*)(wig + c * 1024 + RCOL(F.lane, j)); s += (v[j][0] * w[0] + v[j][1] * w[1]) + (v[j][2] * w[2] + v[j][3] * w[3]); }
;         r[c] = wave_sum(s); if (c & 1) asm volatile("" ::: "memory"); }
.LBB0_1706:
	s_andn2_b64 vcc, exec, s[10:11]
	s_cbranch_vccnz .LBB0_1710
	v_lshl_add_u64 v[238:239], s[58:59], 0, v[72:73]
	s_mov_b64 s[10:11], 0x7680000
	v_cvt_pk_bf16_f32 v240, v24, v25
	v_cvt_pk_bf16_f32 v241, v26, v27
	v_cvt_pk_bf16_f32 v242, v20, v21
	v_cvt_pk_bf16_f32 v243, v22, v23
	v_lshl_add_u64 v[238:239], v[238:239], 0, s[10:11]
	v_cvt_pk_bf16_f32 v244, v28, v29
	v_cvt_pk_bf16_f32 v245, v30, v31
	v_cvt_pk_bf16_f32 v246, v32, v33
	v_cvt_pk_bf16_f32 v247, v34, v35
	global_store_dwordx4 v[238:239], v[240:243], off
	global_store_dwordx4 v[238:239], v[244:247], off offset:1024
	v_lshl_add_u64 v[198:199], s[58:59], 0, v[74:75]
	v_mul_f32_e32 v249, v25, v95
	v_mul_f32_e32 v250, v27, v97
	v_fmac_f32_e32 v249, v24, v94
	v_fmac_f32_e32 v250, v26, v96
	v_add_f32_e32 v249, v249, v250
	v_add_f32_e32 v227, 0, v249
	v_mul_f32_e32 v249, v21, v99
	v_mul_f32_e32 v250, v23, v101
	v_fmac_f32_e32 v249, v20, v98
	v_fmac_f32_e32 v250, v22, v100
	v_add_f32_e32 v249, v249, v250
	v_add_f32_e32 v227, v227, v249
	v_mul_f32_e32 v249, v29, v103
	v_mul_f32_e32 v250, v31, v105
	v_fmac_f32_e32 v249, v28, v102
	v_fmac_f32_e32 v250, v30, v104
	v_add_f32_e32 v249, v249, v250
	v_add_f32_e32 v227, v227, v249
	v_mul_f32_e32 v249, v33, v107
	v_mul_f32_e32 v250, v35, v109
	v_fmac_f32_e32 v249, v32, v106
	v_fmac_f32_e32 v250, v34, v108
	v_add_f32_e32 v249, v249, v250
	v_add_f32_e32 v227, v227, v249
	v_mul_f32_e32 v249, v25, v111
	v_mul_f32_e32 v250, v27, v113
	v_fmac_f32_e32 v249, v24, v110
	v_fmac_f32_e32 v250, v26, v112
	v_add_f32_e32 v249, v249, v250
	v_add_f32_e32 v228, 0, v249
	v_mul_f32_e32 v249, v21, v115
	v_mul_f32_e32 v250, v23, v117
	v_fmac_f32_e32 v249, v20, v114
	v_fmac_f32_e32 v250, v22, v116
	v_add_f32_e32 v249, v249, v250
	v_add_f32_e32 v228, v228, v249
	v_mul_f32_e32 v249, v29, v119
	v_mul_f32_e32 v250, v31, v121
	v_fmac_f32_e32 v249, v28, v118
	v_fmac_f32_e32 v250, v30, v120
	v_add_f32_e32 v249, v249, v250
	v_add_f32_e32 v228, v228, v249
	v_mul_f32_e32 v249, v33, v123
	v_mul_f32_e32 v250, v35, v125
	v_fmac_f32_e32 v249, v32, v122
	v_fmac_f32_e32 v250, v34, v124
	v_add_f32_e32 v249, v249, v250
	v_add_f32_e32 v228, v228, v249
	v_mul_f32_e32 v249, v25, v127
	v_mul_f32_e32 v250, v27, v129
	v_fmac_f32_e32 v249, v24, v126
	v_fmac_f32_e32 v250, v26, v128
	v_add_f32_e32 v249, v249, v250
	v_add_f32_e32 v229, 0, v249
	v_mul_f32_e32 v249, v21, v131
	v_mul_f32_e32 v250, v23, v133
	v_fmac_f32_e32 v249, v20, v130
	v_fmac_f32_e32 v250, v22, v132
	v_add_f32_e32 v249, v249, v250
	v_add_f32_e32 v229, v229, v249
	v_mul_f32_e32 v249, v29, v135
	v_mul_f32_e32 v250, v31, v137
	v_fmac_f32_e32 v249, v28, v134
	v_fmac_f32_e32 v250, v30, v136
	v_add_f32_e32 v249, v249, v250
	v_add_f32_e32 v229, v229, v249
	v_mul_f32_e32 v249, v33, v139
	v_mul_f32_e32 v250, v35, v141
	v_fmac_f32_e32 v249, v32, v138
	v_fmac_f32_e32 v250, v34, v140
	v_add_f32_e32 v249, v249, v250
	v_add_f32_e32 v229, v229, v249
	v_mul_f32_e32 v249, v25, v143
	v_mul_f32_e32 v250, v27, v145
	v_fmac_f32_e32 v249, v24, v142
	v_fmac_f32_e32 v250, v26, v144
	v_add_f32_e32 v249, v249, v250
	v_add_f32_e32 v230, 0, v249
	v_mul_f32_e32 v249, v21, v147
	v_mul_f32_e32 v250, v23, v149
	v_fmac_f32_e32 v249, v20, v146
	v_fmac_f32_e32 v250, v22, v148
	v_add_f32_e32 v249, v249, v250
	v_add_f32_e32 v230, v230, v249
	v_mul_f32_e32 v249, v29, v151
	v_mul_f32_e32 v250, v31, v153
	v_fmac_f32_e32 v249, v28, v150
	v_fmac_f32_e32 v250, v30, v152
	v_add_f32_e32 v249, v249, v250
	v_add_f32_e32 v230, v230, v249
	v_mul_f32_e32 v249, v33, v155
	v_mul_f32_e32 v250, v35, v157
	v_fmac_f32_e32 v249, v32, v154
	v_fmac_f32_e32 v250, v34, v156
	v_add_f32_e32 v249, v249, v250
	v_add_f32_e32 v230, v230, v249
	v_mul_f32_e32 v249, v25, v159
	v_mul_f32_e32 v250, v27, v161
	v_fmac_f32_e32 v249, v24, v158
	v_fmac_f32_e32 v250, v26, v160
	v_add_f32_e32 v249, v249, v250
	v_add_f32_e32 v231, 0, v249
	v_mul_f32_e32 v249, v21, v163
	v_mul_f32_e32 v250, v23, v165
	v_fmac_f32_e32 v249, v20, v162
	v_fmac_f32_e32 v250, v22, v164
	v_add_f32_e32 v249, v249, v250
	v_add_f32_e32 v231, v231, v249
	v_mul_f32_e32 v249, v29, v167
	v_mul_f32_e32 v250, v31, v169
	v_fmac_f32_e32 v249, v28, v166
	v_fmac_f32_e32 v250, v30, v168
	v_add_f32_e32 v249, v249, v250
	v_add_f32_e32 v231, v231, v249
	v_mul_f32_e32 v249, v33, v171
	v_mul_f32_e32 v250, v35, v173
	v_fmac_f32_e32 v249, v32, v170
	v_fmac_f32_e32 v250, v34, v172
	v_add_f32_e32 v249, v249, v250
	v_add_f32_e32 v231, v231, v249
	v_mul_f32_e32 v249, v25, v175
	v_mul_f32_e32 v250, v27, v177
	v_fmac_f32_e32 v249, v24, v174
	v_fmac_f32_e32 v250, v26, v176
	v_add_f32_e32 v249, v249, v250
	v_add_f32_e32 v232, 0, v249
	v_mul_f32_e32 v249, v21, v179
	v_mul_f32_e32 v250, v23, v181
	v_fmac_f32_e32 v249, v20, v178
	v_fmac_f32_e32 v250, v22, v180
	v_add_f32_e32 v249, v249, v250
	v_add_f32_e32 v232, v232, v249
	v_mul_f32_e32 v249, v29, v183
	v_mul_f32_e32 v250, v31, v185
	v_fmac_f32_e32 v249, v28, v182
	v_fmac_f32_e32 v250, v30, v184
	v_add_f32_e32 v249, v249, v250
	v_add_f32_e32 v232, v232, v249
	v_mul_f32_e32 v249, v33, v187
	v_mul_f32_e32 v250, v35, v189
	v_fmac_f32_e32 v249, v32, v186
	v_fmac_f32_e32 v250, v34, v188
	v_add_f32_e32 v249, v249, v250
	v_add_f32_e32 v232, v232, v249
	v_mul_f32_e32 v249, v25, v191
	v_mul_f32_e32 v250, v27, v193
	v_fmac_f32_e32 v249, v24, v190
	v_fmac_f32_e32 v250, v26, v192
	v_add_f32_e32 v249, v249, v250
	v_add_f32_e32 v233, 0, v249
	v_mul_f32_e32 v249, v21, v195
	v_mul_f32_e32 v250, v23, v197
	v_fmac_f32_e32 v249, v20, v194
	v_fmac_f32_e32 v250, v22, v196
	v_add_f32_e32 v249, v249, v250
	v_add_f32_e32 v233, v233, v249
	v_mul_f32_e32 v249, v29, v203
	v_mul_f32_e32 v250, v31, v205
	v_fmac_f32_e32 v249, v28, v202
; template <int CTRL, int ROWMASK> __device__ __forceinline__ float dppf(float v) { return __builtin_bit_cast(float, __builtin_amdgcn_update_dpp(0, __builtin_bit_cast(int, v), CTRL, ROWMASK, 0xf, false)); }
; __device__ __forceinline__ float dpp_sum63(float v) {
;     v += dppf<0xB1, 0xf>(v); v += dppf<0x4E, 0xf>(v); v += dppf<0x141, 0xf>(v); v += dppf<0x140, 0xf>(v);
;     v += dppf<0x142, 0xa>(v); v += dppf<0x143, 0xc>(v); return v;
; }
; template <int CTRL, int ROWMASK> __device__ __forceinline__ float dppm(float v) { return __builtin_bit_cast(float, __builtin_amdgcn_update_dpp(__builtin_bit_cast(int, v), __builtin_bit_cast(int, v), CTRL, ROWMASK, 0xf, false)); }
; __device__ __forceinline__ float rdlane(float v, int l) { return __builtin_bit_cast(float, __builtin_amdgcn_readlane(__builtin_bit_cast(int, v), l)); }
; __device__ __forceinline__ float wave_sum(float v) { return rdlane(dpp_sum63(v), 63); }
; __device__ __forceinline__ void row_finalize(CArgs& A, Frame& F, int m, const f32x4 (&v)[4], int Ln) {
;     ...
;         r[c] = wave_sum(s); if (c & 1) asm volatile("" ::: "memory"); }
;     if (F.lane < 8) { float x = r[0];
; #pragma unroll
;         for (int c = 1; c < 8; ++c) x = (F.lane == c) ? r[c] : x;
;         WSP(float, WS_IGFG)[(size_t)m * 8 + F.lane] = x + b_in[F.lane]; }
	v_fmac_f32_e32 v250, v30, v204
	v_add_f32_e32 v249, v249, v250
	v_add_f32_e32 v233, v233, v249
	v_mul_f32_e32 v249, v33, v207
	v_mul_f32_e32 v250, v35, v209
	v_fmac_f32_e32 v249, v32, v206
	v_fmac_f32_e32 v250, v34, v208
	v_add_f32_e32 v249, v249, v250
	v_add_f32_e32 v233, v233, v249
	v_mul_f32_e32 v249, v25, v211
	v_mul_f32_e32 v250, v27, v213
	v_fmac_f32_e32 v249, v24, v210
	v_fmac_f32_e32 v250, v26, v212
	v_add_f32_e32 v249, v249, v250
	v_add_f32_e32 v248, 0, v249
	v_mul_f32_e32 v249, v21, v215
	v_mul_f32_e32 v250, v23, v217
	v_fmac_f32_e32 v249, v20, v214
	v_fmac_f32_e32 v250, v22, v216
	v_add_f32_e32 v249, v249, v250
	v_add_f32_e32 v248, v248, v249
	v_mul_f32_e32 v249, v29, v219
	v_mul_f32_e32 v250, v31, v221
	v_fmac_f32_e32 v249, v28, v218
	v_fmac_f32_e32 v250, v30, v220
	v_add_f32_e32 v249, v249, v250
	v_add_f32_e32 v248, v248, v249
	v_mul_f32_e32 v249, v33, v223
	v_mul_f32_e32 v250, v35, v225
	v_fmac_f32_e32 v249, v32, v222
	v_fmac_f32_e32 v250, v34, v224
	v_add_f32_e32 v249, v249, v250
	v_add_f32_e32 v248, v248, v249
	v_add_f32_dpp v227, v227, v227 quad_perm:[1,0,3,2] row_mask:0xf bank_mask:0xf bound_ctrl:1
	v_add_f32_dpp v228, v228, v228 quad_perm:[1,0,3,2] row_mask:0xf bank_mask:0xf bound_ctrl:1
	v_add_f32_dpp v229, v229, v229 quad_perm:[1,0,3,2] row_mask:0xf bank_mask:0xf bound_ctrl:1
	v_add_f32_dpp v230, v230, v230 quad_perm:[1,0,3,2] row_mask:0xf bank_mask:0xf bound_ctrl:1
	v_add_f32_dpp v231, v231, v231 quad_perm:[1,0,3,2] row_mask:0xf bank_mask:0xf bound_ctrl:1
	v_add_f32_dpp v232, v232, v232 quad_perm:[1,0,3,2] row_mask:0xf bank_mask:0xf bound_ctrl:1
	v_add_f32_dpp v233, v233, v233 quad_perm:[1,0,3,2] row_mask:0xf bank_mask:0xf bound_ctrl:1
	v_add_f32_dpp v248, v248, v248 quad_perm:[1,0,3,2] row_mask:0xf bank_mask:0xf bound_ctrl:1
	v_add_f32_dpp v227, v227, v227 quad_perm:[2,3,0,1] row_mask:0xf bank_mask:0xf bound_ctrl:1
	v_add_f32_dpp v228, v228, v228 quad_perm:[2,3,0,1] row_mask:0xf bank_mask:0xf bound_ctrl:1
	v_add_f32_dpp v229, v229, v229 quad_perm:[2,3,0,1] row_mask:0xf bank_mask:0xf bound_ctrl:1
	v_add_f32_dpp v230, v230, v230 quad_perm:[2,3,0,1] row_mask:0xf bank_mask:0xf bound_ctrl:1
	v_add_f32_dpp v231, v231, v231 quad_perm:[2,3,0,1] row_mask:0xf bank_mask:0xf bound_ctrl:1
	v_add_f32_dpp v232, v232, v232 quad_perm:[2,3,0,1] row_mask:0xf bank_mask:0xf bound_ctrl:1
	v_add_f32_dpp v233, v233, v233 quad_perm:[2,3,0,1] row_mask:0xf bank_mask:0xf bound_ctrl:1
	v_add_f32_dpp v248, v248, v248 quad_perm:[2,3,0,1] row_mask:0xf bank_mask:0xf bound_ctrl:1
	v_add_f32_dpp v227, v227, v227 row_half_mirror row_mask:0xf bank_mask:0xf bound_ctrl:1
	v_add_f32_dpp v228, v228, v228 row_half_mirror row_mask:0xf bank_mask:0xf bound_ctrl:1
	v_add_f32_dpp v229, v229, v229 row_half_mirror row_mask:0xf bank_mask:0xf bound_ctrl:1
	v_add_f32_dpp v230, v230, v230 row_half_mirror row_mask:0xf bank_mask:0xf bound_ctrl:1
	v_add_f32_dpp v231, v231, v231 row_half_mirror row_mask:0xf bank_mask:0xf bound_ctrl:1
	v_add_f32_dpp v232, v232, v232 row_half_mirror row_mask:0xf bank_mask:0xf bound_ctrl:1
	v_add_f32_dpp v233, v233, v233 row_half_mirror row_mask:0xf bank_mask:0xf bound_ctrl:1
	v_add_f32_dpp v248, v248, v248 row_half_mirror row_mask:0xf bank_mask:0xf bound_ctrl:1
	v_add_f32_dpp v227, v227, v227 row_mirror row_mask:0xf bank_mask:0xf bound_ctrl:1
	v_add_f32_dpp v228, v228, v228 row_mirror row_mask:0xf bank_mask:0xf bound_ctrl:1
	v_add_f32_dpp v229, v229, v229 row_mirror row_mask:0xf bank_mask:0xf bound_ctrl:1
	v_add_f32_dpp v230, v230, v230 row_mirror row_mask:0xf bank_mask:0xf bound_ctrl:1
	v_add_f32_dpp v231, v231, v231 row_mirror row_mask:0xf bank_mask:0xf bound_ctrl:1
	v_add_f32_dpp v232, v232, v232 row_mirror row_mask:0xf bank_mask:0xf bound_ctrl:1
	v_add_f32_dpp v233, v233, v233 row_mirror row_mask:0xf bank_mask:0xf bound_ctrl:1
	v_add_f32_dpp v248, v248, v248 row_mirror row_mask:0xf bank_mask:0xf bound_ctrl:1
	v_add_f32_dpp v227, v227, v227 row_bcast:15 row_mask:0xa bank_mask:0xf
	v_add_f32_dpp v228, v228, v228 row_bcast:15 row_mask:0xa bank_mask:0xf
	v_add_f32_dpp v229, v229, v229 row_bcast:15 row_mask:0xa bank_mask:0xf
	v_add_f32_dpp v230, v230, v230 row_bcast:15 row_mask:0xa bank_mask:0xf
	v_add_f32_dpp v231, v231, v231 row_bcast:15 row_mask:0xa bank_mask:0xf
	v_add_f32_dpp v232, v232, v232 row_bcast:15 row_mask:0xa bank_mask:0xf
	v_add_f32_dpp v233, v233, v233 row_bcast:15 row_mask:0xa bank_mask:0xf
	v_add_f32_dpp v248, v248, v248 row_bcast:15 row_mask:0xa bank_mask:0xf
	v_add_f32_dpp v227, v227, v227 row_bcast:31 row_mask:0xc bank_mask:0xf
	v_add_f32_dpp v228, v228, v228 row_bcast:31 row_mask:0xc bank_mask:0xf
	v_add_f32_dpp v229, v229, v229 row_bcast:31 row_mask:0xc bank_mask:0xf
	v_add_f32_dpp v230, v230, v230 row_bcast:31 row_mask:0xc bank_mask:0xf
	v_add_f32_dpp v231, v231, v231 row_bcast:31 row_mask:0xc bank_mask:0xf
	v_add_f32_dpp v232, v232, v232 row_bcast:31 row_mask:0xc bank_mask:0xf
	v_add_f32_dpp v233, v233, v233 row_bcast:31 row_mask:0xc bank_mask:0xf
	v_add_f32_dpp v248, v248, v248 row_bcast:31 row_mask:0xc bank_mask:0xf
	v_readlane_b32 s28, v227, 63
	v_readlane_b32 s29, v228, 63
	v_readlane_b32 s36, v229, 63
	v_readlane_b32 s37, v230, 63
	v_readlane_b32 s56, v231, 63
	v_readlane_b32 s57, v232, 63
	v_readlane_b32 s60, v233, 63
	v_readlane_b32 s61, v248, 63
	v_writelane_b32 v251, s28, 0
	v_writelane_b32 v251, s29, 1
	v_writelane_b32 v251, s36, 2
	v_writelane_b32 v251, s37, 3
	v_writelane_b32 v251, s56, 4
	v_writelane_b32 v251, s57, 5
	v_writelane_b32 v251, s60, 6
	v_writelane_b32 v251, s61, 7
	s_and_saveexec_b64 s[10:11], s[38:39]
	v_add_f32_e32 v251, v251, v200
	global_store_dword v[198:199], v251, off

; #define LAS __attribute__((address_space(3)))
; __device__ __forceinline__ unsigned pk2(float lo, float hi) { unsigned r; asm volatile("v_cvt_pk_bf16_f32 %0, %1, %2" : "=v"(r) : "v"(lo), "v"(hi)); return r; }
; __device__ __forceinline__ float wave_sum(float v) { return rdlane(dpp_sum63(v), 63); }
; __device__ __forceinline__ void row_store_bf(bf16* p, int lane, const f32x4 (&v)[4]) {
; #pragma unroll
;     for (int j = 0; j < 2; ++j) { u32x4 w; w.x = pk2(v[2 * j][0], v[2 * j][1]); w.y = pk2(v[2 * j][2], v[2 * j][3]); w.z = pk2(v[2 * j + 1][0], v[2 * j + 1][1]); w.w = pk2(v[2 * j + 1][2], v[2 * j + 1][3]); *(u32x4*)(p + 8 * lane + 512 * j) = w; }
; }
; __device__ __forceinline__ void row_finalize(CArgs& A, Frame& F, int m, const f32x4 (&v)[4], int Ln) {
;     row_store_bf(WSP(bf16, WS_X) + (size_t)m * D, F.lane, v);
;     const LAS float* wig = (const LAS float*)(F.lds + WIG_OFF); const float* b_in = A.in[10] + (size_t)Ln * DIN + 3072;
;     float r[8];
; #pragma unroll
;     for (int c = 0; c < 8; ++c) { float s = 0.f;
; #pragma unroll
;         for (int j = 0; j < 4; ++j) { const f32x4 w = *(const LAS f32x4*)(wig + c * 1024 + RCOL(F.lane, j)); s += (v[j][0] * w[0] + v[j][1] * w[1]) + (v[j][2] * w[2] + v[j][3] * w[3]); }
;         r[c] = wave_sum(s); if (c & 1) asm volatile("" ::: "memory"); }
.LBB0_1713:
	s_andn2_b64 vcc, exec, s[10:11]
	s_cbranch_vccnz .LBB0_1717
	v_lshl_add_u64 v[238:239], s[58:59], 0, v[70:71]
	s_mov_b64 s[10:11], 0x7680000
	v_cvt_pk_bf16_f32 v240, v16, v17
	v_cvt_pk_bf16_f32 v241, v18, v19
	v_cvt_pk_bf16_f32 v242, v12, v13
	v_cvt_pk_bf16_f32 v243, v14, v15
	v_lshl_add_u64 v[238:239], v[238:239], 0, s[10:11]
	v_cvt_pk_bf16_f32 v244, v20, v21
	v_cvt_pk_bf16_f32 v245, v22, v23
	v_cvt_pk_bf16_f32 v246, v24, v25
	v_cvt_pk_bf16_f32 v247, v26, v27
	global_store_dwordx4 v[238:239], v[240:243], off
	global_store_dwordx4 v[238:239], v[244:247], off offset:1024
	v_lshl_add_u64 v[198:199], s[58:59], 0, v[68:69]
	v_mul_f32_e32 v249, v17, v95
	v_mul_f32_e32 v250, v19, v97
	v_fmac_f32_e32 v249, v16, v94
	v_fmac_f32_e32 v250, v18, v96
	v_add_f32_e32 v249, v249, v250
	v_add_f32_e32 v227, 0, v249
	v_mul_f32_e32 v249, v13, v99
	v_mul_f32_e32 v250, v15, v101
	v_fmac_f32_e32 v249, v12, v98
	v_fmac_f32_e32 v250, v14, v100
	v_add_f32_e32 v249, v249, v250
	v_add_f32_e32 v227, v227, v249
	v_mul_f32_e32 v249, v21, v103
	v_mul_f32_e32 v250, v23, v105
	v_fmac_f32_e32 v249, v20, v102
	v_fmac_f32_e32 v250, v22, v104
	v_add_f32_e32 v249, v249, v250
	v_add_f32_e32 v227, v227, v249
	v_mul_f32_e32 v249, v25, v107
	v_mul_f32_e32 v250, v27, v109
	v_fmac_f32_e32 v249, v24, v106
	v_fmac_f32_e32 v250, v26, v108
	v_add_f32_e32 v249, v249, v250
	v_add_f32_e32 v227, v227, v249
	v_mul_f32_e32 v249, v17, v111
	v_mul_f32_e32 v250, v19, v113
	v_fmac_f32_e32 v249, v16, v110
	v_fmac_f32_e32 v250, v18, v112
	v_add_f32_e32 v249, v249, v250
	v_add_f32_e32 v228, 0, v249
	v_mul_f32_e32 v249, v13, v115
	v_mul_f32_e32 v250, v15, v117
	v_fmac_f32_e32 v249, v12, v114
	v_fmac_f32_e32 v250, v14, v116
	v_add_f32_e32 v249, v249, v250
	v_add_f32_e32 v228, v228, v249
	v_mul_f32_e32 v249, v21, v119
	v_mul_f32_e32 v250, v23, v121
	v_fmac_f32_e32 v249, v20, v118
	v_fmac_f32_e32 v250, v22, v120
	v_add_f32_e32 v249, v249, v250
	v_add_f32_e32 v228, v228, v249
	v_mul_f32_e32 v249, v25, v123
	v_mul_f32_e32 v250, v27, v125
	v_fmac_f32_e32 v249, v24, v122
	v_fmac_f32_e32 v250, v26, v124
	v_add_f32_e32 v249, v249, v250
	v_add_f32_e32 v228, v228, v249
	v_mul_f32_e32 v249, v17, v127
	v_mul_f32_e32 v250, v19, v129
	v_fmac_f32_e32 v249, v16, v126
	v_fmac_f32_e32 v250, v18, v128
	v_add_f32_e32 v249, v249, v250
	v_add_f32_e32 v229, 0, v249
	v_mul_f32_e32 v249, v13, v131
	v_mul_f32_e32 v250, v15, v133
	v_fmac_f32_e32 v249, v12, v130
	v_fmac_f32_e32 v250, v14, v132
	v_add_f32_e32 v249, v249, v250
	v_add_f32_e32 v229, v229, v249
	v_mul_f32_e32 v249, v21, v135
	v_mul_f32_e32 v250, v23, v137
	v_fmac_f32_e32 v249, v20, v134
	v_fmac_f32_e32 v250, v22, v136
	v_add_f32_e32 v249, v249, v250
	v_add_f32_e32 v229, v229, v249
	v_mul_f32_e32 v249, v25, v139
	v_mul_f32_e32 v250, v27, v141
	v_fmac_f32_e32 v249, v24, v138
	v_fmac_f32_e32 v250, v26, v140
	v_add_f32_e32 v249, v249, v250
	v_add_f32_e32 v229, v229, v249
	v_mul_f32_e32 v249, v17, v143
	v_mul_f32_e32 v250, v19, v145
	v_fmac_f32_e32 v249, v16, v142
	v_fmac_f32_e32 v250, v18, v144
	v_add_f32_e32 v249, v249, v250
	v_add_f32_e32 v230, 0, v249
	v_mul_f32_e32 v249, v13, v147
	v_mul_f32_e32 v250, v15, v149
	v_fmac_f32_e32 v249, v12, v146
	v_fmac_f32_e32 v250, v14, v148
	v_add_f32_e32 v249, v249, v250
	v_add_f32_e32 v230, v230, v249
	v_mul_f32_e32 v249, v21, v151
	v_mul_f32_e32 v250, v23, v153
	v_fmac_f32_e32 v249, v20, v150
	v_fmac_f32_e32 v250, v22, v152
	v_add_f32_e32 v249, v249, v250
	v_add_f32_e32 v230, v230, v249
	v_mul_f32_e32 v249, v25, v155
	v_mul_f32_e32 v250, v27, v157
	v_fmac_f32_e32 v249, v24, v154
	v_fmac_f32_e32 v250, v26, v156
	v_add_f32_e32 v249, v249, v250
	v_add_f32_e32 v230, v230, v249
	v_mul_f32_e32 v249, v17, v159
	v_mul_f32_e32 v250, v19, v161
	v_fmac_f32_e32 v249, v16, v158
	v_fmac_f32_e32 v250, v18, v160
	v_add_f32_e32 v249, v249, v250
	v_add_f32_e32 v231, 0, v249
	v_mul_f32_e32 v249, v13, v163
	v_mul_f32_e32 v250, v15, v165
	v_fmac_f32_e32 v249, v12, v162
	v_fmac_f32_e32 v250, v14, v164
	v_add_f32_e32 v249, v249, v250
	v_add_f32_e32 v231, v231, v249
	v_mul_f32_e32 v249, v21, v167
	v_mul_f32_e32 v250, v23, v169
	v_fmac_f32_e32 v249, v20, v166
	v_fmac_f32_e32 v250, v22, v168
	v_add_f32_e32 v249, v249, v250
	v_add_f32_e32 v231, v231, v249
	v_mul_f32_e32 v249, v25, v171
	v_mul_f32_e32 v250, v27, v173
	v_fmac_f32_e32 v249, v24, v170
	v_fmac_f32_e32 v250, v26, v172
	v_add_f32_e32 v249, v249, v250
	v_add_f32_e32 v231, v231, v249
	v_mul_f32_e32 v249, v17, v175
	v_mul_f32_e32 v250, v19, v177
	v_fmac_f32_e32 v249, v16, v174
	v_fmac_f32_e32 v250, v18, v176
	v_add_f32_e32 v249, v249, v250
	v_add_f32_e32 v232, 0, v249
	v_mul_f32_e32 v249, v13, v179
	v_mul_f32_e32 v250, v15, v181
	v_fmac_f32_e32 v249, v12, v178
	v_fmac_f32_e32 v250, v14, v180
	v_add_f32_e32 v249, v249, v250
	v_add_f32_e32 v232, v232, v249
	v_mul_f32_e32 v249, v21, v183
	v_mul_f32_e32 v250, v23, v185
	v_fmac_f32_e32 v249, v20, v182
	v_fmac_f32_e32 v250, v22, v184
	v_add_f32_e32 v249, v249, v250
	v_add_f32_e32 v232, v232, v249
	v_mul_f32_e32 v249, v25, v187
	v_mul_f32_e32 v250, v27, v189
	v_fmac_f32_e32 v249, v24, v186
	v_fmac_f32_e32 v250, v26, v188
	v_add_f32_e32 v249, v249, v250
	v_add_f32_e32 v232, v232, v249
	v_mul_f32_e32 v249, v17, v191
	v_mul_f32_e32 v250, v19, v193
	v_fmac_f32_e32 v249, v16, v190
	v_fmac_f32_e32 v250, v18, v192
	v_add_f32_e32 v249, v249, v250
	v_add_f32_e32 v233, 0, v249
	v_mul_f32_e32 v249, v13, v195
	v_mul_f32_e32 v250, v15, v197
	v_fmac_f32_e32 v249, v12, v194
	v_fmac_f32_e32 v250, v14, v196
	v_add_f32_e32 v249, v249, v250
	v_add_f32_e32 v233, v233, v249
	v_mul_f32_e32 v249, v21, v203
	v_mul_f32_e32 v250, v23, v205
	v_fmac_f32_e32 v249, v20, v202
; template <int CTRL, int ROWMASK> __device__ __forceinline__ float dppf(float v) { return __builtin_bit_cast(float, __builtin_amdgcn_update_dpp(0, __builtin_bit_cast(int, v), CTRL, ROWMASK, 0xf, false)); }
; __device__ __forceinline__ float dpp_sum63(float v) {
;     v += dppf<0xB1, 0xf>(v); v += dppf<0x4E, 0xf>(v); v += dppf<0x141, 0xf>(v); v += dppf<0x140, 0xf>(v);
;     v += dppf<0x142, 0xa>(v); v += dppf<0x143, 0xc>(v); return v;
; }
; template <int CTRL, int ROWMASK> __device__ __forceinline__ float dppm(float v) { return __builtin_bit_cast(float, __builtin_amdgcn_update_dpp(__builtin_bit_cast(int, v), __builtin_bit_cast(int, v), CTRL, ROWMASK, 0xf, false)); }
; __device__ __forceinline__ float rdlane(float v, int l) { return __builtin_bit_cast(float, __builtin_amdgcn_readlane(__builtin_bit_cast(int, v), l)); }
; __device__ __forceinline__ float wave_sum(float v) { return rdlane(dpp_sum63(v), 63); }
; __device__ __forceinline__ void row_finalize(CArgs& A, Frame& F, int m, const f32x4 (&v)[4], int Ln) {
;     ...
;         r[c] = wave_sum(s); if (c & 1) asm volatile("" ::: "memory"); }
;     if (F.lane < 8) { float x = r[0];
; #pragma unroll
;         for (int c = 1; c < 8; ++c) x = (F.lane == c) ? r[c] : x;
;         WSP(float, WS_IGFG)[(size_t)m * 8 + F.lane] = x + b_in[F.lane]; }
	v_fmac_f32_e32 v250, v22, v204
	v_add_f32_e32 v249, v249, v250
	v_add_f32_e32 v233, v233, v249
	v_mul_f32_e32 v249, v25, v207
	v_mul_f32_e32 v250, v27, v209
	v_fmac_f32_e32 v249, v24, v206
	v_fmac_f32_e32 v250, v26, v208
	v_add_f32_e32 v249, v249, v250
	v_add_f32_e32 v233, v233, v249
	v_mul_f32_e32 v249, v17, v211
	v_mul_f32_e32 v250, v19, v213
	v_fmac_f32_e32 v249, v16, v210
	v_fmac_f32_e32 v250, v18, v212
	v_add_f32_e32 v249, v249, v250
	v_add_f32_e32 v248, 0, v249
	v_mul_f32_e32 v249, v13, v215
	v_mul_f32_e32 v250, v15, v217
	v_fmac_f32_e32 v249, v12, v214
	v_fmac_f32_e32 v250, v14, v216
	v_add_f32_e32 v249, v249, v250
	v_add_f32_e32 v248, v248, v249
	v_mul_f32_e32 v249, v21, v219
	v_mul_f32_e32 v250, v23, v221
	v_fmac_f32_e32 v249, v20, v218
	v_fmac_f32_e32 v250, v22, v220
	v_add_f32_e32 v249, v249, v250
	v_add_f32_e32 v248, v248, v249
	v_mul_f32_e32 v249, v25, v223
	v_mul_f32_e32 v250, v27, v225
	v_fmac_f32_e32 v249, v24, v222
	v_fmac_f32_e32 v250, v26, v224
	v_add_f32_e32 v249, v249, v250
	v_add_f32_e32 v248, v248, v249
	v_add_f32_dpp v227, v227, v227 quad_perm:[1,0,3,2] row_mask:0xf bank_mask:0xf bound_ctrl:1
	v_add_f32_dpp v228, v228, v228 quad_perm:[1,0,3,2] row_mask:0xf bank_mask:0xf bound_ctrl:1
	v_add_f32_dpp v229, v229, v229 quad_perm:[1,0,3,2] row_mask:0xf bank_mask:0xf bound_ctrl:1
	v_add_f32_dpp v230, v230, v230 quad_perm:[1,0,3,2] row_mask:0xf bank_mask:0xf bound_ctrl:1
	v_add_f32_dpp v231, v231, v231 quad_perm:[1,0,3,2] row_mask:0xf bank_mask:0xf bound_ctrl:1
	v_add_f32_dpp v232, v232, v232 quad_perm:[1,0,3,2] row_mask:0xf bank_mask:0xf bound_ctrl:1
	v_add_f32_dpp v233, v233, v233 quad_perm:[1,0,3,2] row_mask:0xf bank_mask:0xf bound_ctrl:1
	v_add_f32_dpp v248, v248, v248 quad_perm:[1,0,3,2] row_mask:0xf bank_mask:0xf bound_ctrl:1
	v_add_f32_dpp v227, v227, v227 quad_perm:[2,3,0,1] row_mask:0xf bank_mask:0xf bound_ctrl:1
	v_add_f32_dpp v228, v228, v228 quad_perm:[2,3,0,1] row_mask:0xf bank_mask:0xf bound_ctrl:1
	v_add_f32_dpp v229, v229, v229 quad_perm:[2,3,0,1] row_mask:0xf bank_mask:0xf bound_ctrl:1
	v_add_f32_dpp v230, v230, v230 quad_perm:[2,3,0,1] row_mask:0xf bank_mask:0xf bound_ctrl:1
	v_add_f32_dpp v231, v231, v231 quad_perm:[2,3,0,1] row_mask:0xf bank_mask:0xf bound_ctrl:1
	v_add_f32_dpp v232, v232, v232 quad_perm:[2,3,0,1] row_mask:0xf bank_mask:0xf bound_ctrl:1
	v_add_f32_dpp v233, v233, v233 quad_perm:[2,3,0,1] row_mask:0xf bank_mask:0xf bound_ctrl:1
	v_add_f32_dpp v248, v248, v248 quad_perm:[2,3,0,1] row_mask:0xf bank_mask:0xf bound_ctrl:1
	v_add_f32_dpp v227, v227, v227 row_half_mirror row_mask:0xf bank_mask:0xf bound_ctrl:1
	v_add_f32_dpp v228, v228, v228 row_half_mirror row_mask:0xf bank_mask:0xf bound_ctrl:1
	v_add_f32_dpp v229, v229, v229 row_half_mirror row_mask:0xf bank_mask:0xf bound_ctrl:1
	v_add_f32_dpp v230, v230, v230 row_half_mirror row_mask:0xf bank_mask:0xf bound_ctrl:1
	v_add_f32_dpp v231, v231, v231 row_half_mirror row_mask:0xf bank_mask:0xf bound_ctrl:1
	v_add_f32_dpp v232, v232, v232 row_half_mirror row_mask:0xf bank_mask:0xf bound_ctrl:1
	v_add_f32_dpp v233, v233, v233 row_half_mirror row_mask:0xf bank_mask:0xf bound_ctrl:1
	v_add_f32_dpp v248, v248, v248 row_half_mirror row_mask:0xf bank_mask:0xf bound_ctrl:1
	v_add_f32_dpp v227, v227, v227 row_mirror row_mask:0xf bank_mask:0xf bound_ctrl:1
	v_add_f32_dpp v228, v228, v228 row_mirror row_mask:0xf bank_mask:0xf bound_ctrl:1
	v_add_f32_dpp v229, v229, v229 row_mirror row_mask:0xf bank_mask:0xf bound_ctrl:1
	v_add_f32_dpp v230, v230, v230 row_mirror row_mask:0xf bank_mask:0xf bound_ctrl:1
	v_add_f32_dpp v231, v231, v231 row_mirror row_mask:0xf bank_mask:0xf bound_ctrl:1
	v_add_f32_dpp v232, v232, v232 row_mirror row_mask:0xf bank_mask:0xf bound_ctrl:1
	v_add_f32_dpp v233, v233, v233 row_mirror row_mask:0xf bank_mask:0xf bound_ctrl:1
	v_add_f32_dpp v248, v248, v248 row_mirror row_mask:0xf bank_mask:0xf bound_ctrl:1
	v_add_f32_dpp v227, v227, v227 row_bcast:15 row_mask:0xa bank_mask:0xf
	v_add_f32_dpp v228, v228, v228 row_bcast:15 row_mask:0xa bank_mask:0xf
	v_add_f32_dpp v229, v229, v229 row_bcast:15 row_mask:0xa bank_mask:0xf
	v_add_f32_dpp v230, v230, v230 row_bcast:15 row_mask:0xa bank_mask:0xf
	v_add_f32_dpp v231, v231, v231 row_bcast:15 row_mask:0xa bank_mask:0xf
	v_add_f32_dpp v232, v232, v232 row_bcast:15 row_mask:0xa bank_mask:0xf
	v_add_f32_dpp v233, v233, v233 row_bcast:15 row_mask:0xa bank_mask:0xf
	v_add_f32_dpp v248, v248, v248 row_bcast:15 row_mask:0xa bank_mask:0xf
	v_add_f32_dpp v227, v227, v227 row_bcast:31 row_mask:0xc bank_mask:0xf
	v_add_f32_dpp v228, v228, v228 row_bcast:31 row_mask:0xc bank_mask:0xf
	v_add_f32_dpp v229, v229, v229 row_bcast:31 row_mask:0xc bank_mask:0xf
	v_add_f32_dpp v230, v230, v230 row_bcast:31 row_mask:0xc bank_mask:0xf
	v_add_f32_dpp v231, v231, v231 row_bcast:31 row_mask:0xc bank_mask:0xf
	v_add_f32_dpp v232, v232, v232 row_bcast:31 row_mask:0xc bank_mask:0xf
	v_add_f32_dpp v233, v233, v233 row_bcast:31 row_mask:0xc bank_mask:0xf
	v_add_f32_dpp v248, v248, v248 row_bcast:31 row_mask:0xc bank_mask:0xf
	v_readlane_b32 s27, v227, 63
	v_readlane_b32 s28, v228, 63
	v_readlane_b32 s29, v229, 63
	v_readlane_b32 s36, v230, 63
	v_readlane_b32 s37, v231, 63
	v_readlane_b32 s56, v232, 63
	v_readlane_b32 s57, v233, 63
	v_readlane_b32 s60, v248, 63
	v_writelane_b32 v251, s27, 0
	v_writelane_b32 v251, s28, 1
	v_writelane_b32 v251, s29, 2
	v_writelane_b32 v251, s36, 3
	v_writelane_b32 v251, s37, 4
	v_writelane_b32 v251, s56, 5
	v_writelane_b32 v251, s57, 6
	v_writelane_b32 v251, s60, 7
	s_and_saveexec_b64 s[10:11], s[38:39]
	v_add_f32_e32 v251, v251, v200
	global_store_dword v[198:199], v251, off

; #define LAS __attribute__((address_space(3)))
; __device__ __forceinline__ unsigned pk2(float lo, float hi) { unsigned r; asm volatile("v_cvt_pk_bf16_f32 %0, %1, %2" : "=v"(r) : "v"(lo), "v"(hi)); return r; }
; __device__ __forceinline__ float wave_sum(float v) { return rdlane(dpp_sum63(v), 63); }
; __device__ __forceinline__ void row_store_bf(bf16* p, int lane, const f32x4 (&v)[4]) {
; #pragma unroll
;     for (int j = 0; j < 2; ++j) { u32x4 w; w.x = pk2(v[2 * j][0], v[2 * j][1]); w.y = pk2(v[2 * j][2], v[2 * j][3]); w.z = pk2(v[2 * j + 1][0], v[2 * j + 1][1]); w.w = pk2(v[2 * j + 1][2], v[2 * j + 1][3]); *(u32x4*)(p + 8 * lane + 512 * j) = w; }
; }
; __device__ __forceinline__ void row_finalize(CArgs& A, Frame& F, int m, const f32x4 (&v)[4], int Ln) {
;     row_store_bf(WSP(bf16, WS_X) + (size_t)m * D, F.lane, v);
;     const LAS float* wig = (const LAS float*)(F.lds + WIG_OFF); const float* b_in = A.in[10] + (size_t)Ln * DIN + 3072;
;     float r[8];
; #pragma unroll
;     for (int c = 0; c < 8; ++c) { float s = 0.f;
; #pragma unroll
;         for (int j = 0; j < 4; ++j) { const f32x4 w = *(const LAS f32x4*)(wig + c * 1024 + RCOL(F.lane, j)); s += (v[j][0] * w[0] + v[j][1] * w[1]) + (v[j][2] * w[2] + v[j][3] * w[3]); }
;         r[c] = wave_sum(s); if (c & 1) asm volatile("" ::: "memory"); }
.LBB0_1720:
	s_andn2_b64 vcc, exec, s[10:11]
	s_cbranch_vccnz .LBB0_1696
	v_lshl_add_u64 v[238:239], s[58:59], 0, v[66:67]
	s_mov_b64 s[10:11], 0x7680000
	v_cvt_pk_bf16_f32 v240, v8, v9
	v_cvt_pk_bf16_f32 v241, v10, v11
	v_cvt_pk_bf16_f32 v242, v4, v5
	v_cvt_pk_bf16_f32 v243, v6, v7
	v_lshl_add_u64 v[238:239], v[238:239], 0, s[10:11]
	v_cvt_pk_bf16_f32 v244, v12, v13
	v_cvt_pk_bf16_f32 v245, v14, v15
	v_cvt_pk_bf16_f32 v246, v16, v17
	v_cvt_pk_bf16_f32 v247, v18, v19
	global_store_dwordx4 v[238:239], v[240:243], off
	global_store_dwordx4 v[238:239], v[244:247], off offset:1024
	v_lshl_add_u64 v[198:199], s[58:59], 0, v[64:65]
	v_mul_f32_e32 v249, v9, v95
	v_mul_f32_e32 v250, v11, v97
	v_fmac_f32_e32 v249, v8, v94
	v_fmac_f32_e32 v250, v10, v96
	v_add_f32_e32 v249, v249, v250
	v_add_f32_e32 v227, 0, v249
	v_mul_f32_e32 v249, v5, v99
	v_mul_f32_e32 v250, v7, v101
	v_fmac_f32_e32 v249, v4, v98
	v_fmac_f32_e32 v250, v6, v100
	v_add_f32_e32 v249, v249, v250
	v_add_f32_e32 v227, v227, v249
	v_mul_f32_e32 v249, v13, v103
	v_mul_f32_e32 v250, v15, v105
	v_fmac_f32_e32 v249, v12, v102
	v_fmac_f32_e32 v250, v14, v104
	v_add_f32_e32 v249, v249, v250
	v_add_f32_e32 v227, v227, v249
	v_mul_f32_e32 v249, v17, v107
	v_mul_f32_e32 v250, v19, v109
	v_fmac_f32_e32 v249, v16, v106
	v_fmac_f32_e32 v250, v18, v108
	v_add_f32_e32 v249, v249, v250
	v_add_f32_e32 v227, v227, v249
	v_mul_f32_e32 v249, v9, v111
	v_mul_f32_e32 v250, v11, v113
	v_fmac_f32_e32 v249, v8, v110
	v_fmac_f32_e32 v250, v10, v112
	v_add_f32_e32 v249, v249, v250
	v_add_f32_e32 v228, 0, v249
	v_mul_f32_e32 v249, v5, v115
	v_mul_f32_e32 v250, v7, v117
	v_fmac_f32_e32 v249, v4, v114
	v_fmac_f32_e32 v250, v6, v116
	v_add_f32_e32 v249, v249, v250
	v_add_f32_e32 v228, v228, v249
	v_mul_f32_e32 v249, v13, v119
	v_mul_f32_e32 v250, v15, v121
	v_fmac_f32_e32 v249, v12, v118
	v_fmac_f32_e32 v250, v14, v120
	v_add_f32_e32 v249, v249, v250
	v_add_f32_e32 v228, v228, v249
	v_mul_f32_e32 v249, v17, v123
	v_mul_f32_e32 v250, v19, v125
	v_fmac_f32_e32 v249, v16, v122
	v_fmac_f32_e32 v250, v18, v124
	v_add_f32_e32 v249, v249, v250
	v_add_f32_e32 v228, v228, v249
	v_mul_f32_e32 v249, v9, v127
	v_mul_f32_e32 v250, v11, v129
	v_fmac_f32_e32 v249, v8, v126
	v_fmac_f32_e32 v250, v10, v128
	v_add_f32_e32 v249, v249, v250
	v_add_f32_e32 v229, 0, v249
	v_mul_f32_e32 v249, v5, v131
	v_mul_f32_e32 v250, v7, v133
	v_fmac_f32_e32 v249, v4, v130
	v_fmac_f32_e32 v250, v6, v132
	v_add_f32_e32 v249, v249, v250
	v_add_f32_e32 v229, v229, v249
	v_mul_f32_e32 v249, v13, v135
	v_mul_f32_e32 v250, v15, v137
	v_fmac_f32_e32 v249, v12, v134
	v_fmac_f32_e32 v250, v14, v136
	v_add_f32_e32 v249, v249, v250
	v_add_f32_e32 v229, v229, v249
	v_mul_f32_e32 v249, v17, v139
	v_mul_f32_e32 v250, v19, v141
	v_fmac_f32_e32 v249, v16, v138
	v_fmac_f32_e32 v250, v18, v140
	v_add_f32_e32 v249, v249, v250
	v_add_f32_e32 v229, v229, v249
	v_mul_f32_e32 v249, v9, v143
	v_mul_f32_e32 v250, v11, v145
	v_fmac_f32_e32 v249, v8, v142
	v_fmac_f32_e32 v250, v10, v144
	v_add_f32_e32 v249, v249, v250
	v_add_f32_e32 v230, 0, v249
	v_mul_f32_e32 v249, v5, v147
	v_mul_f32_e32 v250, v7, v149
	v_fmac_f32_e32 v249, v4, v146
	v_fmac_f32_e32 v250, v6, v148
	v_add_f32_e32 v249, v249, v250
	v_add_f32_e32 v230, v230, v249
	v_mul_f32_e32 v249, v13, v151
	v_mul_f32_e32 v250, v15, v153
	v_fmac_f32_e32 v249, v12, v150
	v_fmac_f32_e32 v250, v14, v152
	v_add_f32_e32 v249, v249, v250
	v_add_f32_e32 v230, v230, v249
	v_mul_f32_e32 v249, v17, v155
	v_mul_f32_e32 v250, v19, v157
	v_fmac_f32_e32 v249, v16, v154
	v_fmac_f32_e32 v250, v18, v156
	v_add_f32_e32 v249, v249, v250
	v_add_f32_e32 v230, v230, v249
	v_mul_f32_e32 v249, v9, v159
	v_mul_f32_e32 v250, v11, v161
	v_fmac_f32_e32 v249, v8, v158
	v_fmac_f32_e32 v250, v10, v160
	v_add_f32_e32 v249, v249, v250
	v_add_f32_e32 v231, 0, v249
	v_mul_f32_e32 v249, v5, v163
	v_mul_f32_e32 v250, v7, v165
	v_fmac_f32_e32 v249, v4, v162
	v_fmac_f32_e32 v250, v6, v164
	v_add_f32_e32 v249, v249, v250
	v_add_f32_e32 v231, v231, v249
	v_mul_f32_e32 v249, v13, v167
	v_mul_f32_e32 v250, v15, v169
	v_fmac_f32_e32 v249, v12, v166
	v_fmac_f32_e32 v250, v14, v168
	v_add_f32_e32 v249, v249, v250
	v_add_f32_e32 v231, v231, v249
	v_mul_f32_e32 v249, v17, v171
	v_mul_f32_e32 v250, v19, v173
	v_fmac_f32_e32 v249, v16, v170
	v_fmac_f32_e32 v250, v18, v172
	v_add_f32_e32 v249, v249, v250
	v_add_f32_e32 v231, v231, v249
	v_mul_f32_e32 v249, v9, v175
	v_mul_f32_e32 v250, v11, v177
	v_fmac_f32_e32 v249, v8, v174
	v_fmac_f32_e32 v250, v10, v176
	v_add_f32_e32 v249, v249, v250
	v_add_f32_e32 v232, 0, v249
	v_mul_f32_e32 v249, v5, v179
	v_mul_f32_e32 v250, v7, v181
	v_fmac_f32_e32 v249, v4, v178
	v_fmac_f32_e32 v250, v6, v180
	v_add_f32_e32 v249, v249, v250
	v_add_f32_e32 v232, v232, v249
	v_mul_f32_e32 v249, v13, v183
	v_mul_f32_e32 v250, v15, v185
	v_fmac_f32_e32 v249, v12, v182
	v_fmac_f32_e32 v250, v14, v184
	v_add_f32_e32 v249, v249, v250
	v_add_f32_e32 v232, v232, v249
	v_mul_f32_e32 v249, v17, v187
	v_mul_f32_e32 v250, v19, v189
	v_fmac_f32_e32 v249, v16, v186
	v_fmac_f32_e32 v250, v18, v188
	v_add_f32_e32 v249, v249, v250
	v_add_f32_e32 v232, v232, v249
	v_mul_f32_e32 v249, v9, v191
	v_mul_f32_e32 v250, v11, v193
	v_fmac_f32_e32 v249, v8, v190
	v_fmac_f32_e32 v250, v10, v192
	v_add_f32_e32 v249, v249, v250
	v_add_f32_e32 v233, 0, v249
	v_mul_f32_e32 v249, v5, v195
	v_mul_f32_e32 v250, v7, v197
	v_fmac_f32_e32 v249, v4, v194
	v_fmac_f32_e32 v250, v6, v196
	v_add_f32_e32 v249, v249, v250
	v_add_f32_e32 v233, v233, v249
	v_mul_f32_e32 v249, v13, v203
	v_mul_f32_e32 v250, v15, v205
	v_fmac_f32_e32 v249, v12, v202
	v_fmac_f32_e32 v250, v14, v204
; template <int CTRL, int ROWMASK> __device__ __forceinline__ float dppf(float v) { return __builtin_bit_cast(float, __builtin_amdgcn_update_dpp(0, __builtin_bit_cast(int, v), CTRL, ROWMASK, 0xf, false)); }
; __device__ __forceinline__ float dpp_sum63(float v) {
;     v += dppf<0xB1, 0xf>(v); v += dppf<0x4E, 0xf>(v); v += dppf<0x141, 0xf>(v); v += dppf<0x140, 0xf>(v);
;     v += dppf<0x142, 0xa>(v); v += dppf<0x143, 0xc>(v); return v;
; }
; template <int CTRL, int ROWMASK> __device__ __forceinline__ float dppm(float v) { return __builtin_bit_cast(float, __builtin_amdgcn_update_dpp(__builtin_bit_cast(int, v), __builtin_bit_cast(int, v), CTRL, ROWMASK, 0xf, false)); }
; __device__ __forceinline__ float rdlane(float v, int l) { return __builtin_bit_cast(float, __builtin_amdgcn_readlane(__builtin_bit_cast(int, v), l)); }
; __device__ __forceinline__ float wave_sum(float v) { return rdlane(dpp_sum63(v), 63); }
; __device__ __forceinline__ void row_finalize(CArgs& A, Frame& F, int m, const f32x4 (&v)[4], int Ln) {
;     ...
;         r[c] = wave_sum(s); if (c & 1) asm volatile("" ::: "memory"); }
;     if (F.lane < 8) { float x = r[0];
; #pragma unroll
;         for (int c = 1; c < 8; ++c) x = (F.lane == c) ? r[c] : x;
;         WSP(float, WS_IGFG)[(size_t)m * 8 + F.lane] = x + b_in[F.lane]; }
; }
	v_add_f32_e32 v249, v249, v250
	v_add_f32_e32 v233, v233, v249
	v_mul_f32_e32 v249, v17, v207
	v_mul_f32_e32 v250, v19, v209
	v_fmac_f32_e32 v249, v16, v206
	v_fmac_f32_e32 v250, v18, v208
	v_add_f32_e32 v249, v249, v250
	v_add_f32_e32 v233, v233, v249
	v_mul_f32_e32 v249, v9, v211
	v_mul_f32_e32 v250, v11, v213
	v_fmac_f32_e32 v249, v8, v210
	v_fmac_f32_e32 v250, v10, v212
	v_add_f32_e32 v249, v249, v250
	v_add_f32_e32 v248, 0, v249
	v_mul_f32_e32 v249, v5, v215
	v_mul_f32_e32 v250, v7, v217
	v_fmac_f32_e32 v249, v4, v214
	v_fmac_f32_e32 v250, v6, v216
	v_add_f32_e32 v249, v249, v250
	v_add_f32_e32 v248, v248, v249
	v_mul_f32_e32 v249, v13, v219
	v_mul_f32_e32 v250, v15, v221
	v_fmac_f32_e32 v249, v12, v218
	v_fmac_f32_e32 v250, v14, v220
	v_add_f32_e32 v249, v249, v250
	v_add_f32_e32 v248, v248, v249
	v_mul_f32_e32 v249, v17, v223
	v_mul_f32_e32 v250, v19, v225
	v_fmac_f32_e32 v249, v16, v222
	v_fmac_f32_e32 v250, v18, v224
	v_add_f32_e32 v249, v249, v250
	v_add_f32_e32 v248, v248, v249
	v_add_f32_dpp v227, v227, v227 quad_perm:[1,0,3,2] row_mask:0xf bank_mask:0xf bound_ctrl:1
	v_add_f32_dpp v228, v228, v228 quad_perm:[1,0,3,2] row_mask:0xf bank_mask:0xf bound_ctrl:1
	v_add_f32_dpp v229, v229, v229 quad_perm:[1,0,3,2] row_mask:0xf bank_mask:0xf bound_ctrl:1
	v_add_f32_dpp v230, v230, v230 quad_perm:[1,0,3,2] row_mask:0xf bank_mask:0xf bound_ctrl:1
	v_add_f32_dpp v231, v231, v231 quad_perm:[1,0,3,2] row_mask:0xf bank_mask:0xf bound_ctrl:1
	v_add_f32_dpp v232, v232, v232 quad_perm:[1,0,3,2] row_mask:0xf bank_mask:0xf bound_ctrl:1
	v_add_f32_dpp v233, v233, v233 quad_perm:[1,0,3,2] row_mask:0xf bank_mask:0xf bound_ctrl:1
	v_add_f32_dpp v248, v248, v248 quad_perm:[1,0,3,2] row_mask:0xf bank_mask:0xf bound_ctrl:1
	v_add_f32_dpp v227, v227, v227 quad_perm:[2,3,0,1] row_mask:0xf bank_mask:0xf bound_ctrl:1
	v_add_f32_dpp v228, v228, v228 quad_perm:[2,3,0,1] row_mask:0xf bank_mask:0xf bound_ctrl:1
	v_add_f32_dpp v229, v229, v229 quad_perm:[2,3,0,1] row_mask:0xf bank_mask:0xf bound_ctrl:1
	v_add_f32_dpp v230, v230, v230 quad_perm:[2,3,0,1] row_mask:0xf bank_mask:0xf bound_ctrl:1
	v_add_f32_dpp v231, v231, v231 quad_perm:[2,3,0,1] row_mask:0xf bank_mask:0xf bound_ctrl:1
	v_add_f32_dpp v232, v232, v232 quad_perm:[2,3,0,1] row_mask:0xf bank_mask:0xf bound_ctrl:1
	v_add_f32_dpp v233, v233, v233 quad_perm:[2,3,0,1] row_mask:0xf bank_mask:0xf bound_ctrl:1
	v_add_f32_dpp v248, v248, v248 quad_perm:[2,3,0,1] row_mask:0xf bank_mask:0xf bound_ctrl:1
	v_add_f32_dpp v227, v227, v227 row_half_mirror row_mask:0xf bank_mask:0xf bound_ctrl:1
	v_add_f32_dpp v228, v228, v228 row_half_mirror row_mask:0xf bank_mask:0xf bound_ctrl:1
	v_add_f32_dpp v229, v229, v229 row_half_mirror row_mask:0xf bank_mask:0xf bound_ctrl:1
	v_add_f32_dpp v230, v230, v230 row_half_mirror row_mask:0xf bank_mask:0xf bound_ctrl:1
	v_add_f32_dpp v231, v231, v231 row_half_mirror row_mask:0xf bank_mask:0xf bound_ctrl:1
	v_add_f32_dpp v232, v232, v232 row_half_mirror row_mask:0xf bank_mask:0xf bound_ctrl:1
	v_add_f32_dpp v233, v233, v233 row_half_mirror row_mask:0xf bank_mask:0xf bound_ctrl:1
	v_add_f32_dpp v248, v248, v248 row_half_mirror row_mask:0xf bank_mask:0xf bound_ctrl:1
	v_add_f32_dpp v227, v227, v227 row_mirror row_mask:0xf bank_mask:0xf bound_ctrl:1
	v_add_f32_dpp v228, v228, v228 row_mirror row_mask:0xf bank_mask:0xf bound_ctrl:1
	v_add_f32_dpp v229, v229, v229 row_mirror row_mask:0xf bank_mask:0xf bound_ctrl:1
	v_add_f32_dpp v230, v230, v230 row_mirror row_mask:0xf bank_mask:0xf bound_ctrl:1
	v_add_f32_dpp v231, v231, v231 row_mirror row_mask:0xf bank_mask:0xf bound_ctrl:1
	v_add_f32_dpp v232, v232, v232 row_mirror row_mask:0xf bank_mask:0xf bound_ctrl:1
	v_add_f32_dpp v233, v233, v233 row_mirror row_mask:0xf bank_mask:0xf bound_ctrl:1
	v_add_f32_dpp v248, v248, v248 row_mirror row_mask:0xf bank_mask:0xf bound_ctrl:1
	v_add_f32_dpp v227, v227, v227 row_bcast:15 row_mask:0xa bank_mask:0xf
	v_add_f32_dpp v228, v228, v228 row_bcast:15 row_mask:0xa bank_mask:0xf
	v_add_f32_dpp v229, v229, v229 row_bcast:15 row_mask:0xa bank_mask:0xf
	v_add_f32_dpp v230, v230, v230 row_bcast:15 row_mask:0xa bank_mask:0xf
	v_add_f32_dpp v231, v231, v231 row_bcast:15 row_mask:0xa bank_mask:0xf
	v_add_f32_dpp v232, v232, v232 row_bcast:15 row_mask:0xa bank_mask:0xf
	v_add_f32_dpp v233, v233, v233 row_bcast:15 row_mask:0xa bank_mask:0xf
	v_add_f32_dpp v248, v248, v248 row_bcast:15 row_mask:0xa bank_mask:0xf
	v_add_f32_dpp v227, v227, v227 row_bcast:31 row_mask:0xc bank_mask:0xf
	v_add_f32_dpp v228, v228, v228 row_bcast:31 row_mask:0xc bank_mask:0xf
	v_add_f32_dpp v229, v229, v229 row_bcast:31 row_mask:0xc bank_mask:0xf
	v_add_f32_dpp v230, v230, v230 row_bcast:31 row_mask:0xc bank_mask:0xf
	v_add_f32_dpp v231, v231, v231 row_bcast:31 row_mask:0xc bank_mask:0xf
	v_add_f32_dpp v232, v232, v232 row_bcast:31 row_mask:0xc bank_mask:0xf
	v_add_f32_dpp v233, v233, v233 row_bcast:31 row_mask:0xc bank_mask:0xf
	v_add_f32_dpp v248, v248, v248 row_bcast:31 row_mask:0xc bank_mask:0xf
	v_readlane_b32 s7, v227, 63
	v_readlane_b32 s27, v228, 63
	v_readlane_b32 s28, v229, 63
	v_readlane_b32 s29, v230, 63
	v_readlane_b32 s36, v231, 63
	v_readlane_b32 s37, v232, 63
	v_readlane_b32 s54, v233, 63
	v_readlane_b32 s55, v248, 63
	v_writelane_b32 v251, s7, 0
	v_writelane_b32 v251, s27, 1
	v_writelane_b32 v251, s28, 2
	v_writelane_b32 v251, s29, 3
	v_writelane_b32 v251, s36, 4
	v_writelane_b32 v251, s37, 5
	v_writelane_b32 v251, s54, 6
	v_writelane_b32 v251, s55, 7
	s_and_saveexec_b64 s[10:11], s[38:39]
	v_add_f32_e32 v251, v251, v200
	global_store_dword v[198:199], v251, off
	s_branch .LBB0_1695
